# v9 plus first K-loop iteration after a tile epilogue skips the phase-1/2 vmcnt(8) waits in the input-projection and gate-up GEMMs
# baseline (speedup 1.0000x reference)
;     __device__ bool next(int i, Unit& u) const {
;         const long L = (long)i * G + c; if (L >= nwg || c >= G) return false;
;         int wgid = (int)L; { const int q = nwg / NXCD, r = nwg % NXCD, xcd = wgid % NXCD, off = wgid / NXCD; wgid = (xcd < r ? xcd * (q + 1) : r * (q + 1) + (xcd - r) * q) + off; }
;         const int nig = WGM * nN, gid = wgid / nig, fm = gid * WGM, gsz = (nM - fm) < WGM ? (nM - fm) : WGM;
;         u.pm = fm + ((wgid % nig) % gsz); u.pn = (wgid % nig) / gsz; u.aoff = 0; u.gi = 0; return true;
; __global__ void __launch_bounds__(512, 2) mega(Args args) {
;     ...
;         int bx_ = blockIdx.x; asm volatile("" : "+s"(bx_)); const int bx = bx_, vcu = (bx % 8) * (G / 8) + bx / 8;
;         unsigned char* ws = args.ws; asm volatile("" : "+s"(ws));
;         constexpr int NGW = G * 8;
;         const float* x_in = (const float*)args.in[0]; const float* mem = (const float*)args.in[1]; const int* positions = (const int*)args.in[2];
;         float* xcur = args.out;
;         float* ssb = (float*)(ws + WS_SS); float* qssb = (float*)(ws + WS_QSS); float* lsumb = (float*)(ws + WS_LSUM); float* kssb = (float*)(ws + WS_KSS); float* ssmem = (float*)(ws + WS_SSMEM);
;         float* cs = (float*)(ws + WS_CS); float* xsh = (float*)(ws + WS_XSH);
;         bf16_t* memb = (bf16_t*)(ws + WS_MEMB); bf16_t* mkraw = (bf16_t*)(ws + WS_MKRAW); bf16_t* mvT = (bf16_t*)(ws + WS_MVT);
;         bf16_t* Win_t = (bf16_t*)(ws + WS_WIN); bf16_t* Wc_t = (bf16_t*)(ws + WS_WC); bf16_t* Wd_t = (bf16_t*)(ws + WS_WD); bf16_t* Wx_t = (bf16_t*)(ws + WS_WX);
;         bf16_t* Wmkv_t = (bf16_t*)(ws + WS_WMKV); bf16_t* Wo_t = (bf16_t*)(ws + WS_WO); bf16_t* Wgu_t = (bf16_t*)(ws + WS_WGU); bf16_t* Wdn_t = (bf16_t*)(ws + WS_WDN);
;         bf16_t* proj = (bf16_t*)(ws + WS_PROJ); bf16_t* VT = (bf16_t*)(ws + WS_VT); bf16_t* xb = (bf16_t*)(ws + WS_XB); bf16_t* mg = (bf16_t*)(ws + WS_MG); bf16_t* hb = (bf16_t*)(ws + WS_H);
;         const int l = ph >> 3, p = ph & 7;
;         const int wave = wave0, gw = vcu * 8 + wave;
;     ...
;         const float* gq_x = (const float*)args.in[14] + l * 256; const float* gk_x = (const float*)args.in[15] + l * 256;
;         float* qss = qssb + (size_t)l * TOK * 4; float* lsum = lsumb + (size_t)l * TOK * 4; float* kss = kssb + l * 2048;
;         if (p == 0) {
.LBB1_13:
	s_mov_b32 s100, 0
	v_readlane_b32 s88, v252, 0
	s_ashr_i32 s4, s88, 31
	s_mov_b64 s[96:97], s[44:45]
	v_writelane_b32 v255, s4, 0
	s_lshr_b32 s4, s4, 29
	s_add_i32 s4, s88, s4
	s_ashr_i32 s21, s4, 3
	s_and_b32 s4, s4, -8
	s_sub_i32 s19, s88, s4
	s_add_u32 s4, s96, 0x3c00000
	s_addc_u32 s5, s97, 0
	v_writelane_b32 v255, s4, 1
	s_mov_b32 s68, s42
	s_nop 0
	v_writelane_b32 v255, s5, 2
	s_add_u32 s4, s96, 0x5000000
	s_addc_u32 s5, s97, 0
	s_add_u32 s86, s96, 0x5800000
	v_writelane_b32 v255, s4, 3
	s_addc_u32 s87, s97, 0
	s_nop 0
	v_writelane_b32 v255, s5, 4
	s_add_u32 s4, s96, 0x8400000
	s_addc_u32 s5, s97, 0
	s_add_u32 s6, s96, 0x9a00000
	s_addc_u32 s7, s97, 0
	v_writelane_b32 v255, s4, 5
	s_add_u32 s34, s96, 0x23a00000
	s_addc_u32 s35, s97, 0
	v_writelane_b32 v255, s5, 6
	s_ashr_i32 s4, s42, 3
	s_ashr_i32 s5, s4, 31
	s_and_b32 s63, s42, 7
	v_writelane_b32 v255, s4, 7
	s_cmp_lt_i32 s63, 4
	s_nop 0
	v_writelane_b32 v255, s5, 8
	s_mov_b64 s[4:5], -1
	s_cbranch_scc1 .LBB1_262
	s_cmp_lt_i32 s63, 6
	s_cbranch_scc1 .LBB1_95
	s_cmp_gt_i32 s63, 6
	s_cbranch_scc0 .LBB1_76
	v_readlane_b32 s4, v252, 14
	v_readlane_b32 s5, v252, 15
	s_mov_b32 s23, s63
	s_mov_b32 s22, s19
	s_mov_b32 s20, s68
	s_andn2_b64 vcc, exec, s[4:5]
	v_mbcnt_lo_u32_b32 v0, -1, 0
	v_mbcnt_hi_u32_b32 v0, -1, v0
	s_cbranch_vccnz .LBB1_75
	v_readlane_b32 s8, v252, 13
	s_cmpk_lt_i32 s88, 0x100
	v_mbcnt_lo_u32_b32 v14, -1, 0
	v_mbcnt_hi_u32_b32 v14, -1, v14
	s_cselect_b64 s[4:5], -1, 0
	v_or_b32_e32 v0, s8, v14
	s_cmpk_gt_i32 s88, 0xff
	v_readfirstlane_b32 s14, v0
	s_cbranch_scc1 .LBB1_19
	s_lshl_b32 s9, s22, 6
	s_mul_i32 s8, s22, 0x41
	s_cmp_lt_i32 s22, 0
	s_cselect_b32 s8, s8, s9
	s_add_i32 s8, s8, s21
	s_ashr_i32 s9, s8, 31
	s_lshr_b32 s9, s9, 26
	s_add_i32 s9, s8, s9
	s_ashr_i32 s15, s9, 6
	s_lshl_b32 s15, s15, 3
	s_sub_i32 s26, 64, s15
	s_min_i32 s26, s26, 8
	s_abs_i32 s27, s26
	v_cvt_f32_u32_e32 v2, s27
	s_sub_i32 s37, 0, s27
	s_andn2_b32 s9, s9, 63
	s_sub_i32 s8, s8, s9
	v_rcp_iflag_f32_e32 v2, v2
	s_abs_i32 s9, s8
	s_xor_b32 s36, s8, s26
	s_ashr_i32 s36, s36, 31
	v_mul_f32_e32 v2, 0x4f7ffffe, v2
	v_cvt_u32_f32_e32 v2, v2
	s_nop 0
	v_readfirstlane_b32 s38, v2
	s_mul_i32 s37, s37, s38
	s_mul_hi_u32 s37, s38, s37
	s_add_i32 s38, s38, s37
	s_mul_hi_u32 s37, s9, s38
	s_mul_i32 s38, s37, s27
	s_sub_i32 s9, s9, s38
	s_add_i32 s39, s37, 1
	s_sub_i32 s38, s9, s27
	s_cmp_ge_u32 s9, s27
	s_cselect_b32 s37, s39, s37
	s_cselect_b32 s9, s38, s9
	s_add_i32 s38, s37, 1
	s_cmp_ge_u32 s9, s27
	s_cselect_b32 s9, s38, s37
	s_xor_b32 s9, s9, s36
	s_sub_i32 s69, s9, s36
	s_mul_i32 s9, s69, s26
	s_sub_i32 s8, s8, s9
	s_add_i32 s70, s15, s8

; #define PG8_STAGE(bufoff, gbase, voff) do { _Pragma("unroll") for (int _i = 0; _i < 2; ++_i) \
;         __builtin_amdgcn_global_load_lds((const unsigned*)((const char*)(gbase) + (voff)[_i]), (LAS unsigned*)(lds + (bufoff) + ldsw + _i * 8192), 16, 0, 0); } while (0)
; #define PG8_LDA(dst, b, h) do { _Pragma("unroll") for (int m = 0; m < 4; ++m) _Pragma("unroll") for (int k = 0; k < 2; ++k) dst[m][k] = *(const LAS bf16x8*)(lds + PG8_SA(b, h) + aoff + m * 2048 + k * 1024); } while (0)
; #define PG8_LDB(dst, b, h) do { _Pragma("unroll") for (int n = 0; n < 2; ++n) _Pragma("unroll") for (int k = 0; k < 2; ++k) dst[n][k] = *(const LAS bf16x8*)(lds + PG8_SB(b, h) + boff + n * 2048 + k * 1024); } while (0)
; #define PG8_MMA(ai, bj, At, Bt) do { __builtin_amdgcn_s_setprio(1); _Pragma("unroll") for (int m = 0; m < 4; ++m) _Pragma("unroll") for (int n = 0; n < 2; ++n) _Pragma("unroll") for (int k = 0; k < 2; ++k) \
;         acc[ai][bj][m][n] = __builtin_amdgcn_mfma_f32_16x16x32_bf16(Bt[n][k], At[m][k], acc[ai][bj][m][n], 0, 0, 0); __builtin_amdgcn_s_setprio(0); } while (0)
; #define PG8_WAIT_V(n) asm volatile("s_waitcnt vmcnt(" #n ")" ::: "memory")
; #define PG8_WAIT_L(n) asm volatile("s_waitcnt lgkmcnt(" #n ")" ::: "memory")
; #define PG8_BAR __builtin_amdgcn_s_barrier()
; #define PG8_SCHED __builtin_amdgcn_sched_barrier(0)
; template <class Epi, class Sched>
; __device__ __forceinline__ void gemm_phase(LAS unsigned char* lds, const Gemm g, const Sched& S, const Epi& E, const int tid) {
;     ...
;         for (int t = 0; t < nt; t += 2) {
;             const bool last = (t == nt - 2);
;             const char* a1 = cA + (size_t)(t + 1) * kstep;
;             const char* a2 = last ? nA : cA + (size_t)(t + 2) * kstep; const char* b2 = last ? nB : cB + (size_t)(t + 2) * kstep;
;             const char* a3 = a2 + kstep; const char* b3 = b2 + kstep;
;             PG8_LDB(B0, 0, 0); PG8_LDB(B1, 0, 1); PG8_SCHED; PG8_LDA(At, 0, 0); PG8_STAGE(PG8_SA(1, 1), a1 + hstepA, voffA);
;             PG8_WAIT_V(8); PG8_WAIT_L(0); PG8_BAR; PG8_MMA(0, 0, At, B0); PG8_MMA(0, 1, At, B1); PG8_BAR; PG8_SCHED;
;             PG8_LDA(At, 0, 1); PG8_STAGE(PG8_SB(0, 0), b2, voffB); PG8_STAGE(PG8_SB(0, 1), b2 + hstepB, voffB); PG8_STAGE(PG8_SA(0, 0), a2, voffA);
;             PG8_WAIT_V(8); PG8_WAIT_L(0); PG8_BAR; PG8_MMA(1, 0, At, B0); PG8_MMA(1, 1, At, B1); PG8_BAR; PG8_SCHED;
.LBB1_87:
	s_add_u32 s14, s58, 0xfff80080
	s_addc_u32 s15, s59, -1
	s_add_i32 s70, 0, 0x10000
	s_cmp_eq_u32 s45, 28
	s_cselect_b32 s63, s37, s15
	s_cselect_b32 s62, s53, s14
	v_add_u32_e32 v144, s70, v147
	s_cselect_b32 s61, s41, s44
	s_cselect_b32 s60, s68, s69
	s_add_i32 s71, 0, 0x14000
	ds_read_b128 v[140:143], v144
	ds_read_b128 v[158:161], v144 offset:1024
	ds_read_b128 v[162:165], v144 offset:2048
	ds_read_b128 v[166:169], v144 offset:3072
	v_add_u32_e32 v144, s71, v147
	ds_read_b128 v[170:173], v144
	ds_read_b128 v[174:177], v144 offset:1024
	ds_read_b128 v[178:181], v144 offset:2048
	ds_read_b128 v[182:185], v144 offset:3072
	v_lshl_add_u64 v[220:221], s[58:59], 0, v[138:139]
	s_add_i32 m0, s47, 0xc000
	ds_read_b128 v[186:189], v157
	ds_read_b128 v[190:193], v157 offset:1024
	ds_read_b128 v[194:197], v157 offset:2048
	ds_read_b128 v[198:201], v157 offset:3072
	ds_read_b128 v[204:207], v157 offset:4096
	ds_read_b128 v[208:211], v157 offset:5120
	ds_read_b128 v[212:215], v157 offset:6144
	ds_read_b128 v[216:219], v157 offset:7168
	global_load_lds_dwordx4 v[220:221], off
	v_lshl_add_u64 v[220:221], s[58:59], 0, v[136:137]
	s_add_i32 m0, s47, 0xe000
	s_nop 0
	global_load_lds_dwordx4 v[220:221], off
	s_cmp_lg_u32 s100, 0
	s_cbranch_scc1 .Lt1_87_1
	s_waitcnt vmcnt(8)
.Lt1_87_1:
	s_waitcnt lgkmcnt(0)
	s_barrier
	s_setprio 1
	s_waitcnt lgkmcnt(0)
	v_mfma_f32_16x16x32_bf16 v[126:129], v[140:143], v[186:189], v[126:129]
	v_mfma_f32_16x16x32_bf16 v[118:121], v[162:165], v[186:189], v[118:121]
	v_mfma_f32_16x16x32_bf16 v[110:113], v[140:143], v[194:197], v[110:113]
	v_mfma_f32_16x16x32_bf16 v[106:109], v[162:165], v[194:197], v[106:109]
	v_mfma_f32_16x16x32_bf16 v[94:97], v[140:143], v[204:207], v[94:97]
	v_mfma_f32_16x16x32_bf16 v[90:93], v[162:165], v[204:207], v[90:93]
	v_mfma_f32_16x16x32_bf16 v[78:81], v[140:143], v[212:215], v[78:81]
	v_mfma_f32_16x16x32_bf16 v[74:77], v[162:165], v[212:215], v[74:77]
	v_mfma_f32_16x16x32_bf16 v[126:129], v[158:161], v[190:193], v[126:129]
	v_mfma_f32_16x16x32_bf16 v[118:121], v[166:169], v[190:193], v[118:121]
	v_mfma_f32_16x16x32_bf16 v[110:113], v[158:161], v[198:201], v[110:113]
	v_mfma_f32_16x16x32_bf16 v[106:109], v[166:169], v[198:201], v[106:109]
	v_mfma_f32_16x16x32_bf16 v[94:97], v[158:161], v[208:211], v[94:97]
	v_mfma_f32_16x16x32_bf16 v[90:93], v[166:169], v[208:211], v[90:93]
	v_mfma_f32_16x16x32_bf16 v[78:81], v[158:161], v[216:219], v[78:81]
	v_mfma_f32_16x16x32_bf16 v[74:77], v[166:169], v[216:219], v[74:77]
	s_setprio 0
	s_setprio 1
	v_mfma_f32_16x16x32_bf16 v[122:125], v[170:173], v[186:189], v[122:125]
	v_mfma_f32_16x16x32_bf16 v[114:117], v[178:181], v[186:189], v[114:117]
	v_mfma_f32_16x16x32_bf16 v[102:105], v[170:173], v[194:197], v[102:105]
	v_mfma_f32_16x16x32_bf16 v[98:101], v[178:181], v[194:197], v[98:101]
	v_mfma_f32_16x16x32_bf16 v[86:89], v[170:173], v[204:207], v[86:89]
	v_mfma_f32_16x16x32_bf16 v[82:85], v[178:181], v[204:207], v[82:85]
	v_mfma_f32_16x16x32_bf16 v[70:73], v[170:173], v[212:215], v[70:73]
	v_mfma_f32_16x16x32_bf16 v[66:69], v[178:181], v[212:215], v[66:69]
	v_mfma_f32_16x16x32_bf16 v[122:125], v[174:177], v[190:193], v[122:125]
	v_mfma_f32_16x16x32_bf16 v[114:117], v[182:185], v[190:193], v[114:117]
	v_mfma_f32_16x16x32_bf16 v[102:105], v[174:177], v[198:201], v[102:105]
	v_mfma_f32_16x16x32_bf16 v[98:101], v[182:185], v[198:201], v[98:101]
	v_mfma_f32_16x16x32_bf16 v[86:89], v[174:177], v[208:211], v[86:89]
	v_mfma_f32_16x16x32_bf16 v[82:85], v[182:185], v[208:211], v[82:85]
	v_mfma_f32_16x16x32_bf16 v[70:73], v[174:177], v[216:219], v[70:73]
	v_mfma_f32_16x16x32_bf16 v[66:69], v[182:185], v[216:219], v[66:69]
	s_setprio 0
	s_barrier
	s_add_i32 s14, s70, s46
	v_lshl_add_u64 v[220:221], s[60:61], 0, v[0:1]
	s_mov_b32 m0, s14
	ds_read_b128 v[186:189], v157 offset:16384
	ds_read_b128 v[190:193], v157 offset:17408
	ds_read_b128 v[194:197], v157 offset:18432
	ds_read_b128 v[198:201], v157 offset:19456
	ds_read_b128 v[204:207], v157 offset:20480
	ds_read_b128 v[208:211], v157 offset:21504
	ds_read_b128 v[212:215], v157 offset:22528
	ds_read_b128 v[216:219], v157 offset:23552
	global_load_lds_dwordx4 v[220:221], off
	s_add_i32 m0, s14, 0x2000
	s_add_u32 s14, s60, 0x80000
	v_lshl_add_u64 v[222:223], s[60:61], 0, v[130:131]
	s_addc_u32 s15, s61, 0
	s_add_i32 s70, s71, s46
	global_load_lds_dwordx4 v[222:223], off
	v_lshl_add_u64 v[224:225], s[14:15], 0, v[0:1]
	s_mov_b32 m0, s70
	v_lshl_add_u64 v[226:227], s[62:63], 0, v[132:133]
	global_load_lds_dwordx4 v[224:225], off
	v_lshl_add_u64 v[224:225], s[14:15], 0, v[130:131]
	s_add_i32 m0, s70, 0x2000
	s_nop 0
	global_load_lds_dwordx4 v[224:225], off
	v_lshl_add_u64 v[224:225], s[62:63], 0, v[134:135]
	s_mov_b32 m0, s47
	s_nop 0
	global_load_lds_dwordx4 v[224:225], off
	s_mov_b32 m0, s57
	s_nop 0
	global_load_lds_dwordx4 v[226:227], off
	s_cmp_lg_u32 s100, 0
	s_cbranch_scc1 .Lt1_87_2
	s_waitcnt vmcnt(8)
; #define PG8_STAGE(bufoff, gbase, voff) do { _Pragma("unroll") for (int _i = 0; _i < 2; ++_i) \
;         __builtin_amdgcn_global_load_lds((const unsigned*)((const char*)(gbase) + (voff)[_i]), (LAS unsigned*)(lds + (bufoff) + ldsw + _i * 8192), 16, 0, 0); } while (0)
; #define PG8_LDA(dst, b, h) do { _Pragma("unroll") for (int m = 0; m < 4; ++m) _Pragma("unroll") for (int k = 0; k < 2; ++k) dst[m][k] = *(const LAS bf16x8*)(lds + PG8_SA(b, h) + aoff + m * 2048 + k * 1024); } while (0)
; #define PG8_LDB(dst, b, h) do { _Pragma("unroll") for (int n = 0; n < 2; ++n) _Pragma("unroll") for (int k = 0; k < 2; ++k) dst[n][k] = *(const LAS bf16x8*)(lds + PG8_SB(b, h) + boff + n * 2048 + k * 1024); } while (0)
; #define PG8_MMA(ai, bj, At, Bt) do { __builtin_amdgcn_s_setprio(1); _Pragma("unroll") for (int m = 0; m < 4; ++m) _Pragma("unroll") for (int n = 0; n < 2; ++n) _Pragma("unroll") for (int k = 0; k < 2; ++k) \
;         acc[ai][bj][m][n] = __builtin_amdgcn_mfma_f32_16x16x32_bf16(Bt[n][k], At[m][k], acc[ai][bj][m][n], 0, 0, 0); __builtin_amdgcn_s_setprio(0); } while (0)
; #define PG8_WAIT_V(n) asm volatile("s_waitcnt vmcnt(" #n ")" ::: "memory")
; #define PG8_WAIT_L(n) asm volatile("s_waitcnt lgkmcnt(" #n ")" ::: "memory")
; #define PG8_BAR __builtin_amdgcn_s_barrier()
; #define PG8_SCHED __builtin_amdgcn_sched_barrier(0)
; template <class Epi, class Sched>
; __device__ __forceinline__ void gemm_phase(LAS unsigned char* lds, const Gemm g, const Sched& S, const Epi& E, const int tid) {
;     ...
;             PG8_WAIT_V(8); PG8_WAIT_L(0); PG8_BAR; PG8_MMA(1, 0, At, B0); PG8_MMA(1, 1, At, B1); PG8_BAR; PG8_SCHED;
;             PG8_LDB(B0, 1, 0); PG8_LDB(B1, 1, 1); PG8_SCHED; PG8_LDA(At, 1, 0); PG8_STAGE(PG8_SA(0, 1), a2 + hstepA, voffA);
;             PG8_WAIT_V(8); PG8_WAIT_L(0); PG8_BAR; PG8_MMA(0, 0, At, B0); PG8_MMA(0, 1, At, B1); PG8_BAR; PG8_SCHED;
.Lt1_87_2:
	s_mov_b32 s100, 0
	s_waitcnt lgkmcnt(0)
	s_barrier
	s_setprio 1
	s_waitcnt lgkmcnt(0)
	v_mfma_f32_16x16x32_bf16 v[62:65], v[140:143], v[186:189], v[62:65]
	v_mfma_f32_16x16x32_bf16 v[58:61], v[162:165], v[186:189], v[58:61]
	v_mfma_f32_16x16x32_bf16 v[46:49], v[140:143], v[194:197], v[46:49]
	v_mfma_f32_16x16x32_bf16 v[42:45], v[162:165], v[194:197], v[42:45]
	v_mfma_f32_16x16x32_bf16 v[30:33], v[140:143], v[204:207], v[30:33]
	v_mfma_f32_16x16x32_bf16 v[26:29], v[162:165], v[204:207], v[26:29]
	v_mfma_f32_16x16x32_bf16 v[14:17], v[140:143], v[212:215], v[14:17]
	v_mfma_f32_16x16x32_bf16 v[10:13], v[162:165], v[212:215], v[10:13]
	v_mfma_f32_16x16x32_bf16 v[62:65], v[158:161], v[190:193], v[62:65]
	v_mfma_f32_16x16x32_bf16 v[58:61], v[166:169], v[190:193], v[58:61]
	v_mfma_f32_16x16x32_bf16 v[46:49], v[158:161], v[198:201], v[46:49]
	v_mfma_f32_16x16x32_bf16 v[42:45], v[166:169], v[198:201], v[42:45]
	v_mfma_f32_16x16x32_bf16 v[30:33], v[158:161], v[208:211], v[30:33]
	v_mfma_f32_16x16x32_bf16 v[26:29], v[166:169], v[208:211], v[26:29]
	v_mfma_f32_16x16x32_bf16 v[14:17], v[158:161], v[216:219], v[14:17]
	v_mfma_f32_16x16x32_bf16 v[10:13], v[166:169], v[216:219], v[10:13]
	s_setprio 0
	s_setprio 1
	v_mfma_f32_16x16x32_bf16 v[54:57], v[170:173], v[186:189], v[54:57]
	v_mfma_f32_16x16x32_bf16 v[50:53], v[178:181], v[186:189], v[50:53]
	v_mfma_f32_16x16x32_bf16 v[38:41], v[170:173], v[194:197], v[38:41]
	v_mfma_f32_16x16x32_bf16 v[34:37], v[178:181], v[194:197], v[34:37]
	v_mfma_f32_16x16x32_bf16 v[22:25], v[170:173], v[204:207], v[22:25]
	v_mfma_f32_16x16x32_bf16 v[18:21], v[178:181], v[204:207], v[18:21]
	v_mfma_f32_16x16x32_bf16 v[6:9], v[170:173], v[212:215], v[6:9]
	v_mfma_f32_16x16x32_bf16 v[2:5], v[178:181], v[212:215], v[2:5]
	v_mfma_f32_16x16x32_bf16 v[54:57], v[174:177], v[190:193], v[54:57]
	v_mfma_f32_16x16x32_bf16 v[50:53], v[182:185], v[190:193], v[50:53]
	v_mfma_f32_16x16x32_bf16 v[38:41], v[174:177], v[198:201], v[38:41]
	v_mfma_f32_16x16x32_bf16 v[34:37], v[182:185], v[198:201], v[34:37]
	v_mfma_f32_16x16x32_bf16 v[22:25], v[174:177], v[208:211], v[22:25]
	v_mfma_f32_16x16x32_bf16 v[18:21], v[182:185], v[208:211], v[18:21]
	v_mfma_f32_16x16x32_bf16 v[6:9], v[174:177], v[216:219], v[6:9]
	v_mfma_f32_16x16x32_bf16 v[2:5], v[182:185], v[216:219], v[2:5]
	s_setprio 0
	s_barrier
	s_add_i32 s70, 0, 0x18000
	v_add_u32_e32 v144, s70, v147
	s_add_i32 s71, 0, 0x1c000
	ds_read_b128 v[140:143], v144
	ds_read_b128 v[158:161], v144 offset:1024
	ds_read_b128 v[162:165], v144 offset:2048
	ds_read_b128 v[166:169], v144 offset:3072
	v_add_u32_e32 v144, s71, v147
	ds_read_b128 v[170:173], v144
	ds_read_b128 v[174:177], v144 offset:1024
	ds_read_b128 v[178:181], v144 offset:2048
	ds_read_b128 v[182:185], v144 offset:3072
	s_add_u32 s14, s62, 0x80000
	s_addc_u32 s15, s63, 0
	s_mov_b32 m0, s64
	v_lshl_add_u64 v[228:229], s[14:15], 0, v[134:135]
	ds_read_b128 v[186:189], v157 offset:32768
	ds_read_b128 v[190:193], v157 offset:33792
	ds_read_b128 v[194:197], v157 offset:34816
	ds_read_b128 v[198:201], v157 offset:35840
	ds_read_b128 v[204:207], v157 offset:36864
	ds_read_b128 v[208:211], v157 offset:37888
	ds_read_b128 v[212:215], v157 offset:38912
	ds_read_b128 v[216:219], v157 offset:39936
	global_load_lds_dwordx4 v[228:229], off
	v_lshl_add_u64 v[228:229], s[14:15], 0, v[132:133]
	s_mov_b32 m0, s65
	s_nop 0
	global_load_lds_dwordx4 v[228:229], off
	s_waitcnt vmcnt(8)
	s_waitcnt lgkmcnt(0)
	s_barrier
	s_setprio 1
	s_waitcnt lgkmcnt(0)
	v_mfma_f32_16x16x32_bf16 v[126:129], v[140:143], v[186:189], v[126:129]
	v_mfma_f32_16x16x32_bf16 v[118:121], v[162:165], v[186:189], v[118:121]
	v_mfma_f32_16x16x32_bf16 v[110:113], v[140:143], v[194:197], v[110:113]
	v_mfma_f32_16x16x32_bf16 v[106:109], v[162:165], v[194:197], v[106:109]
	v_mfma_f32_16x16x32_bf16 v[94:97], v[140:143], v[204:207], v[94:97]
	v_mfma_f32_16x16x32_bf16 v[90:93], v[162:165], v[204:207], v[90:93]
	v_mfma_f32_16x16x32_bf16 v[78:81], v[140:143], v[212:215], v[78:81]
	v_mfma_f32_16x16x32_bf16 v[74:77], v[162:165], v[212:215], v[74:77]
	v_mfma_f32_16x16x32_bf16 v[126:129], v[158:161], v[190:193], v[126:129]
	v_mfma_f32_16x16x32_bf16 v[118:121], v[166:169], v[190:193], v[118:121]
	v_mfma_f32_16x16x32_bf16 v[110:113], v[158:161], v[198:201], v[110:113]
	v_mfma_f32_16x16x32_bf16 v[106:109], v[166:169], v[198:201], v[106:109]
	v_mfma_f32_16x16x32_bf16 v[94:97], v[158:161], v[208:211], v[94:97]
	v_mfma_f32_16x16x32_bf16 v[90:93], v[166:169], v[208:211], v[90:93]
	v_mfma_f32_16x16x32_bf16 v[78:81], v[158:161], v[216:219], v[78:81]
	v_mfma_f32_16x16x32_bf16 v[74:77], v[166:169], v[216:219], v[74:77]
	s_setprio 0
	s_setprio 1
	v_mfma_f32_16x16x32_bf16 v[122:125], v[170:173], v[186:189], v[122:125]
	v_mfma_f32_16x16x32_bf16 v[114:117], v[178:181], v[186:189], v[114:117]
	v_mfma_f32_16x16x32_bf16 v[102:105], v[170:173], v[194:197], v[102:105]
	v_mfma_f32_16x16x32_bf16 v[98:101], v[178:181], v[194:197], v[98:101]
	v_mfma_f32_16x16x32_bf16 v[86:89], v[170:173], v[204:207], v[86:89]
	v_mfma_f32_16x16x32_bf16 v[82:85], v[178:181], v[204:207], v[82:85]
	v_mfma_f32_16x16x32_bf16 v[70:73], v[170:173], v[212:215], v[70:73]
	v_mfma_f32_16x16x32_bf16 v[66:69], v[178:181], v[212:215], v[66:69]
	v_mfma_f32_16x16x32_bf16 v[122:125], v[174:177], v[190:193], v[122:125]
	v_mfma_f32_16x16x32_bf16 v[114:117], v[182:185], v[190:193], v[114:117]
	v_mfma_f32_16x16x32_bf16 v[102:105], v[174:177], v[198:201], v[102:105]
	v_mfma_f32_16x16x32_bf16 v[98:101], v[182:185], v[198:201], v[98:101]
	v_mfma_f32_16x16x32_bf16 v[86:89], v[174:177], v[208:211], v[86:89]
	v_mfma_f32_16x16x32_bf16 v[82:85], v[182:185], v[208:211], v[82:85]
	v_mfma_f32_16x16x32_bf16 v[70:73], v[174:177], v[216:219], v[70:73]
	v_mfma_f32_16x16x32_bf16 v[66:69], v[182:185], v[216:219], v[66:69]
	s_setprio 0
	s_barrier
; #define PG8_STAGE(bufoff, gbase, voff) do { _Pragma("unroll") for (int _i = 0; _i < 2; ++_i) \
;         __builtin_amdgcn_global_load_lds((const unsigned*)((const char*)(gbase) + (voff)[_i]), (LAS unsigned*)(lds + (bufoff) + ldsw + _i * 8192), 16, 0, 0); } while (0)
; #define PG8_LDA(dst, b, h) do { _Pragma("unroll") for (int m = 0; m < 4; ++m) _Pragma("unroll") for (int k = 0; k < 2; ++k) dst[m][k] = *(const LAS bf16x8*)(lds + PG8_SA(b, h) + aoff + m * 2048 + k * 1024); } while (0)
; #define PG8_MMA(ai, bj, At, Bt) do { __builtin_amdgcn_s_setprio(1); _Pragma("unroll") for (int m = 0; m < 4; ++m) _Pragma("unroll") for (int n = 0; n < 2; ++n) _Pragma("unroll") for (int k = 0; k < 2; ++k) \
;         acc[ai][bj][m][n] = __builtin_amdgcn_mfma_f32_16x16x32_bf16(Bt[n][k], At[m][k], acc[ai][bj][m][n], 0, 0, 0); __builtin_amdgcn_s_setprio(0); } while (0)
; #define PG8_WAIT_V(n) asm volatile("s_waitcnt vmcnt(" #n ")" ::: "memory")
; #define PG8_WAIT_L(n) asm volatile("s_waitcnt lgkmcnt(" #n ")" ::: "memory")
; #define PG8_BAR __builtin_amdgcn_s_barrier()
; #define PG8_SCHED __builtin_amdgcn_sched_barrier(0)
; template <class Epi, class Sched>
; __device__ __forceinline__ void gemm_phase(LAS unsigned char* lds, const Gemm g, const Sched& S, const Epi& E, const int tid) {
;     ...
;             PG8_LDA(At, 1, 1); PG8_STAGE(PG8_SB(1, 0), b3, voffB); PG8_STAGE(PG8_SB(1, 1), b3 + hstepB, voffB); PG8_STAGE(PG8_SA(1, 0), a3, voffA);
;             PG8_WAIT_V(8); PG8_WAIT_L(0); PG8_BAR; PG8_MMA(1, 0, At, B0); PG8_MMA(1, 1, At, B1); PG8_BAR; PG8_SCHED;
;         }
;         if (wr == 0) PG8_BAR;
;         E(acc, cur, wr, wc, fr, fq);
;         if (!has_next) break;
;         if (E.zero_after(cur))
	s_add_i32 s14, s70, s46
	v_lshl_add_u64 v[220:221], v[220:221], 0, s[90:91]
	s_mov_b32 m0, s14
	ds_read_b128 v[186:189], v157 offset:49152
	ds_read_b128 v[190:193], v157 offset:50176
	ds_read_b128 v[194:197], v157 offset:51200
	ds_read_b128 v[198:201], v157 offset:52224
	ds_read_b128 v[204:207], v157 offset:53248
	ds_read_b128 v[208:211], v157 offset:54272
	ds_read_b128 v[212:215], v157 offset:55296
	ds_read_b128 v[216:219], v157 offset:56320
	global_load_lds_dwordx4 v[220:221], off
	s_add_i32 m0, s14, 0x2000
	s_add_u32 s14, s60, 0x80080
	v_lshl_add_u64 v[220:221], v[222:223], 0, s[90:91]
	s_addc_u32 s15, s61, 0
	s_add_i32 s60, s71, s46
	global_load_lds_dwordx4 v[220:221], off
	v_lshl_add_u64 v[220:221], s[14:15], 0, v[0:1]
	s_mov_b32 m0, s60
	s_nop 0
	global_load_lds_dwordx4 v[220:221], off
	v_lshl_add_u64 v[220:221], s[14:15], 0, v[130:131]
	s_add_i32 m0, s60, 0x2000
	s_nop 0
	global_load_lds_dwordx4 v[220:221], off
	v_lshl_add_u64 v[220:221], v[224:225], 0, s[90:91]
	s_mov_b32 m0, s66
	s_nop 0
	global_load_lds_dwordx4 v[220:221], off
	v_lshl_add_u64 v[220:221], v[226:227], 0, s[90:91]
	s_mov_b32 m0, s67
	s_nop 0
	global_load_lds_dwordx4 v[220:221], off
	s_waitcnt vmcnt(8)
	s_waitcnt lgkmcnt(0)
	s_barrier
	s_setprio 1
	s_waitcnt lgkmcnt(0)
	v_mfma_f32_16x16x32_bf16 v[62:65], v[140:143], v[186:189], v[62:65]
	v_mfma_f32_16x16x32_bf16 v[58:61], v[162:165], v[186:189], v[58:61]
	v_mfma_f32_16x16x32_bf16 v[46:49], v[140:143], v[194:197], v[46:49]
	v_mfma_f32_16x16x32_bf16 v[42:45], v[162:165], v[194:197], v[42:45]
	v_mfma_f32_16x16x32_bf16 v[30:33], v[140:143], v[204:207], v[30:33]
	v_mfma_f32_16x16x32_bf16 v[26:29], v[162:165], v[204:207], v[26:29]
	v_mfma_f32_16x16x32_bf16 v[14:17], v[140:143], v[212:215], v[14:17]
	v_mfma_f32_16x16x32_bf16 v[10:13], v[162:165], v[212:215], v[10:13]
	v_mfma_f32_16x16x32_bf16 v[62:65], v[158:161], v[190:193], v[62:65]
	v_mfma_f32_16x16x32_bf16 v[58:61], v[166:169], v[190:193], v[58:61]
	v_mfma_f32_16x16x32_bf16 v[46:49], v[158:161], v[198:201], v[46:49]
	v_mfma_f32_16x16x32_bf16 v[42:45], v[166:169], v[198:201], v[42:45]
	v_mfma_f32_16x16x32_bf16 v[30:33], v[158:161], v[208:211], v[30:33]
	v_mfma_f32_16x16x32_bf16 v[26:29], v[166:169], v[208:211], v[26:29]
	v_mfma_f32_16x16x32_bf16 v[14:17], v[158:161], v[216:219], v[14:17]
	v_mfma_f32_16x16x32_bf16 v[10:13], v[166:169], v[216:219], v[10:13]
	s_setprio 0
	s_setprio 1
	v_mfma_f32_16x16x32_bf16 v[54:57], v[170:173], v[186:189], v[54:57]
	v_mfma_f32_16x16x32_bf16 v[50:53], v[178:181], v[186:189], v[50:53]
	v_mfma_f32_16x16x32_bf16 v[38:41], v[170:173], v[194:197], v[38:41]
	v_mfma_f32_16x16x32_bf16 v[34:37], v[178:181], v[194:197], v[34:37]
	v_mfma_f32_16x16x32_bf16 v[22:25], v[170:173], v[204:207], v[22:25]
	v_mfma_f32_16x16x32_bf16 v[18:21], v[178:181], v[204:207], v[18:21]
	v_mfma_f32_16x16x32_bf16 v[6:9], v[170:173], v[212:215], v[6:9]
	v_mfma_f32_16x16x32_bf16 v[2:5], v[178:181], v[212:215], v[2:5]
	v_mfma_f32_16x16x32_bf16 v[54:57], v[174:177], v[190:193], v[54:57]
	v_mfma_f32_16x16x32_bf16 v[50:53], v[182:185], v[190:193], v[50:53]
	v_mfma_f32_16x16x32_bf16 v[38:41], v[174:177], v[198:201], v[38:41]
	v_mfma_f32_16x16x32_bf16 v[34:37], v[182:185], v[198:201], v[34:37]
	v_mfma_f32_16x16x32_bf16 v[22:25], v[174:177], v[208:211], v[22:25]
	v_mfma_f32_16x16x32_bf16 v[18:21], v[182:185], v[208:211], v[18:21]
	v_mfma_f32_16x16x32_bf16 v[6:9], v[174:177], v[216:219], v[6:9]
	v_mfma_f32_16x16x32_bf16 v[2:5], v[182:185], v[216:219], v[2:5]
	s_setprio 0
	s_barrier
	s_add_i32 s45, s45, 2
	s_add_u32 s69, s69, 0x100
	s_addc_u32 s44, s44, 0
	s_add_u32 s58, s58, 0x100
	s_addc_u32 s59, s59, 0
	s_cmp_gt_u32 s45, 29
	s_cbranch_scc0 .LBB1_87
	s_mov_b32 s100, 1
	s_and_b64 vcc, exec, s[26:27]
	s_cbranch_vccz .LBB1_90
	s_barrier

; #define PG8_STAGE(bufoff, gbase, voff) do { _Pragma("unroll") for (int _i = 0; _i < 2; ++_i) \
;         __builtin_amdgcn_global_load_lds((const unsigned*)((const char*)(gbase) + (voff)[_i]), (LAS unsigned*)(lds + (bufoff) + ldsw + _i * 8192), 16, 0, 0); } while (0)
; #define PG8_LDA(dst, b, h) do { _Pragma("unroll") for (int m = 0; m < 4; ++m) _Pragma("unroll") for (int k = 0; k < 2; ++k) dst[m][k] = *(const LAS bf16x8*)(lds + PG8_SA(b, h) + aoff + m * 2048 + k * 1024); } while (0)
; #define PG8_LDB(dst, b, h) do { _Pragma("unroll") for (int n = 0; n < 2; ++n) _Pragma("unroll") for (int k = 0; k < 2; ++k) dst[n][k] = *(const LAS bf16x8*)(lds + PG8_SB(b, h) + boff + n * 2048 + k * 1024); } while (0)
; #define PG8_MMA(ai, bj, At, Bt) do { __builtin_amdgcn_s_setprio(1); _Pragma("unroll") for (int m = 0; m < 4; ++m) _Pragma("unroll") for (int n = 0; n < 2; ++n) _Pragma("unroll") for (int k = 0; k < 2; ++k) \
;         acc[ai][bj][m][n] = __builtin_amdgcn_mfma_f32_16x16x32_bf16(Bt[n][k], At[m][k], acc[ai][bj][m][n], 0, 0, 0); __builtin_amdgcn_s_setprio(0); } while (0)
; #define PG8_WAIT_V(n) asm volatile("s_waitcnt vmcnt(" #n ")" ::: "memory")
; #define PG8_WAIT_L(n) asm volatile("s_waitcnt lgkmcnt(" #n ")" ::: "memory")
; #define PG8_BAR __builtin_amdgcn_s_barrier()
; #define PG8_SCHED __builtin_amdgcn_sched_barrier(0)
; template <class Epi, class Sched>
; __device__ __forceinline__ void gemm_phase(LAS unsigned char* lds, const Gemm g, const Sched& S, const Epi& E, const int tid) {
;     ...
;         for (int t = 0; t < nt; t += 2) {
;             const bool last = (t == nt - 2);
;             const char* a1 = cA + (size_t)(t + 1) * kstep;
;             const char* a2 = last ? nA : cA + (size_t)(t + 2) * kstep; const char* b2 = last ? nB : cB + (size_t)(t + 2) * kstep;
;             const char* a3 = a2 + kstep; const char* b3 = b2 + kstep;
;             PG8_LDB(B0, 0, 0); PG8_LDB(B1, 0, 1); PG8_SCHED; PG8_LDA(At, 0, 0); PG8_STAGE(PG8_SA(1, 1), a1 + hstepA, voffA);
;             PG8_WAIT_V(8); PG8_WAIT_L(0); PG8_BAR; PG8_MMA(0, 0, At, B0); PG8_MMA(0, 1, At, B1); PG8_BAR; PG8_SCHED;
;             PG8_LDA(At, 0, 1); PG8_STAGE(PG8_SB(0, 0), b2, voffB); PG8_STAGE(PG8_SB(0, 1), b2 + hstepB, voffB); PG8_STAGE(PG8_SA(0, 0), a2, voffA);
;             PG8_WAIT_V(8); PG8_WAIT_L(0); PG8_BAR; PG8_MMA(1, 0, At, B0); PG8_MMA(1, 1, At, B1); PG8_BAR; PG8_SCHED;
.LBB1_574:
	s_add_u32 s14, s44, 0xfff80080
	s_addc_u32 s15, s45, -1
	s_add_i32 s82, 0, 0x10000
	s_cmp_eq_u32 s81, 28
	s_cselect_b32 s73, s43, s15
	s_cselect_b32 s72, s47, s14
	v_add_u32_e32 v148, s82, v151
	s_cselect_b32 s71, s61, s80
	s_cselect_b32 s70, s65, s79
	s_add_i32 s83, 0, 0x14000
	ds_read_b128 v[144:147], v148
	ds_read_b128 v[158:161], v148 offset:1024
	ds_read_b128 v[162:165], v148 offset:2048
	ds_read_b128 v[166:169], v148 offset:3072
	v_add_u32_e32 v148, s83, v151
	ds_read_b128 v[170:173], v148
	ds_read_b128 v[174:177], v148 offset:1024
	ds_read_b128 v[178:181], v148 offset:2048
	ds_read_b128 v[182:185], v148 offset:3072
	v_lshl_add_u64 v[148:149], s[44:45], 0, v[142:143]
	s_add_i32 m0, s57, 0xc000
	ds_read_b128 v[186:189], v156
	ds_read_b128 v[190:193], v156 offset:1024
	ds_read_b128 v[204:207], v156 offset:2048
	ds_read_b128 v[208:211], v156 offset:3072
	ds_read_b128 v[212:215], v156 offset:4096
	ds_read_b128 v[216:219], v156 offset:5120
	ds_read_b128 v[220:223], v156 offset:6144
	ds_read_b128 v[230:233], v156 offset:7168
	global_load_lds_dwordx4 v[148:149], off
	v_lshl_add_u64 v[148:149], s[44:45], 0, v[140:141]
	s_add_i32 m0, s57, 0xe000
	s_nop 0
	global_load_lds_dwordx4 v[148:149], off
	s_cmp_lg_u32 s100, 0
	s_cbranch_scc1 .Lt1_574_1
	s_waitcnt vmcnt(8)
.Lt1_574_1:
	s_waitcnt lgkmcnt(0)
	s_barrier
	s_setprio 1
	s_waitcnt lgkmcnt(0)
	v_mfma_f32_16x16x32_bf16 v[126:129], v[144:147], v[186:189], v[126:129]
	v_mfma_f32_16x16x32_bf16 v[122:125], v[162:165], v[186:189], v[122:125]
	v_mfma_f32_16x16x32_bf16 v[110:113], v[144:147], v[204:207], v[110:113]
	v_mfma_f32_16x16x32_bf16 v[106:109], v[162:165], v[204:207], v[106:109]
	v_mfma_f32_16x16x32_bf16 v[94:97], v[144:147], v[212:215], v[94:97]
	v_mfma_f32_16x16x32_bf16 v[90:93], v[162:165], v[212:215], v[90:93]
	v_mfma_f32_16x16x32_bf16 v[78:81], v[144:147], v[220:223], v[78:81]
	v_mfma_f32_16x16x32_bf16 v[74:77], v[162:165], v[220:223], v[74:77]
	v_mfma_f32_16x16x32_bf16 v[126:129], v[158:161], v[190:193], v[126:129]
	v_mfma_f32_16x16x32_bf16 v[122:125], v[166:169], v[190:193], v[122:125]
	v_mfma_f32_16x16x32_bf16 v[110:113], v[158:161], v[208:211], v[110:113]
	v_mfma_f32_16x16x32_bf16 v[106:109], v[166:169], v[208:211], v[106:109]
	v_mfma_f32_16x16x32_bf16 v[94:97], v[158:161], v[216:219], v[94:97]
	v_mfma_f32_16x16x32_bf16 v[90:93], v[166:169], v[216:219], v[90:93]
	v_mfma_f32_16x16x32_bf16 v[78:81], v[158:161], v[230:233], v[78:81]
	v_mfma_f32_16x16x32_bf16 v[74:77], v[166:169], v[230:233], v[74:77]
	s_setprio 0
	s_setprio 1
	v_mfma_f32_16x16x32_bf16 v[118:121], v[170:173], v[186:189], v[118:121]
	v_mfma_f32_16x16x32_bf16 v[114:117], v[178:181], v[186:189], v[114:117]
	v_mfma_f32_16x16x32_bf16 v[102:105], v[170:173], v[204:207], v[102:105]
	v_mfma_f32_16x16x32_bf16 v[98:101], v[178:181], v[204:207], v[98:101]
	v_mfma_f32_16x16x32_bf16 v[86:89], v[170:173], v[212:215], v[86:89]
	v_mfma_f32_16x16x32_bf16 v[82:85], v[178:181], v[212:215], v[82:85]
	v_mfma_f32_16x16x32_bf16 v[70:73], v[170:173], v[220:223], v[70:73]
	v_mfma_f32_16x16x32_bf16 v[66:69], v[178:181], v[220:223], v[66:69]
	v_mfma_f32_16x16x32_bf16 v[118:121], v[174:177], v[190:193], v[118:121]
	v_mfma_f32_16x16x32_bf16 v[114:117], v[182:185], v[190:193], v[114:117]
	v_mfma_f32_16x16x32_bf16 v[102:105], v[174:177], v[208:211], v[102:105]
	v_mfma_f32_16x16x32_bf16 v[98:101], v[182:185], v[208:211], v[98:101]
	v_mfma_f32_16x16x32_bf16 v[86:89], v[174:177], v[216:219], v[86:89]
	v_mfma_f32_16x16x32_bf16 v[82:85], v[182:185], v[216:219], v[82:85]
	v_mfma_f32_16x16x32_bf16 v[70:73], v[174:177], v[230:233], v[70:73]
	v_mfma_f32_16x16x32_bf16 v[66:69], v[182:185], v[230:233], v[66:69]
	s_setprio 0
	s_barrier
	s_add_i32 s14, s82, s56
	v_lshl_add_u64 v[148:149], s[70:71], 0, v[0:1]
	s_mov_b32 m0, s14
	ds_read_b128 v[186:189], v156 offset:16384
	ds_read_b128 v[190:193], v156 offset:17408
	ds_read_b128 v[204:207], v156 offset:18432
	ds_read_b128 v[208:211], v156 offset:19456
	ds_read_b128 v[212:215], v156 offset:20480
	ds_read_b128 v[216:219], v156 offset:21504
	ds_read_b128 v[220:223], v156 offset:22528
	ds_read_b128 v[230:233], v156 offset:23552
	global_load_lds_dwordx4 v[148:149], off
	s_add_i32 m0, s14, 0x2000
	s_add_u32 s14, s70, 0x80000
	v_lshl_add_u64 v[194:195], s[70:71], 0, v[134:135]
	s_addc_u32 s15, s71, 0
	s_add_i32 s82, s83, s56
	global_load_lds_dwordx4 v[194:195], off
	v_lshl_add_u64 v[196:197], s[14:15], 0, v[0:1]
	s_mov_b32 m0, s82
	v_lshl_add_u64 v[198:199], s[72:73], 0, v[132:133]
	global_load_lds_dwordx4 v[196:197], off
	v_lshl_add_u64 v[196:197], s[14:15], 0, v[134:135]
	s_add_i32 m0, s82, 0x2000
	s_nop 0
	global_load_lds_dwordx4 v[196:197], off
	v_lshl_add_u64 v[196:197], s[72:73], 0, v[130:131]
	s_mov_b32 m0, s57
	s_nop 0
	global_load_lds_dwordx4 v[196:197], off
	s_mov_b32 m0, s74
	s_nop 0
	global_load_lds_dwordx4 v[198:199], off
	s_cmp_lg_u32 s100, 0
	s_cbranch_scc1 .Lt1_574_2
	s_waitcnt vmcnt(8)
; #define PG8_STAGE(bufoff, gbase, voff) do { _Pragma("unroll") for (int _i = 0; _i < 2; ++_i) \
;         __builtin_amdgcn_global_load_lds((const unsigned*)((const char*)(gbase) + (voff)[_i]), (LAS unsigned*)(lds + (bufoff) + ldsw + _i * 8192), 16, 0, 0); } while (0)
; #define PG8_LDA(dst, b, h) do { _Pragma("unroll") for (int m = 0; m < 4; ++m) _Pragma("unroll") for (int k = 0; k < 2; ++k) dst[m][k] = *(const LAS bf16x8*)(lds + PG8_SA(b, h) + aoff + m * 2048 + k * 1024); } while (0)
; #define PG8_LDB(dst, b, h) do { _Pragma("unroll") for (int n = 0; n < 2; ++n) _Pragma("unroll") for (int k = 0; k < 2; ++k) dst[n][k] = *(const LAS bf16x8*)(lds + PG8_SB(b, h) + boff + n * 2048 + k * 1024); } while (0)
; #define PG8_MMA(ai, bj, At, Bt) do { __builtin_amdgcn_s_setprio(1); _Pragma("unroll") for (int m = 0; m < 4; ++m) _Pragma("unroll") for (int n = 0; n < 2; ++n) _Pragma("unroll") for (int k = 0; k < 2; ++k) \
;         acc[ai][bj][m][n] = __builtin_amdgcn_mfma_f32_16x16x32_bf16(Bt[n][k], At[m][k], acc[ai][bj][m][n], 0, 0, 0); __builtin_amdgcn_s_setprio(0); } while (0)
; #define PG8_WAIT_V(n) asm volatile("s_waitcnt vmcnt(" #n ")" ::: "memory")
; #define PG8_WAIT_L(n) asm volatile("s_waitcnt lgkmcnt(" #n ")" ::: "memory")
; #define PG8_BAR __builtin_amdgcn_s_barrier()
; #define PG8_SCHED __builtin_amdgcn_sched_barrier(0)
; template <class Epi, class Sched>
; __device__ __forceinline__ void gemm_phase(LAS unsigned char* lds, const Gemm g, const Sched& S, const Epi& E, const int tid) {
;     ...
;             PG8_WAIT_V(8); PG8_WAIT_L(0); PG8_BAR; PG8_MMA(1, 0, At, B0); PG8_MMA(1, 1, At, B1); PG8_BAR; PG8_SCHED;
;             PG8_LDB(B0, 1, 0); PG8_LDB(B1, 1, 1); PG8_SCHED; PG8_LDA(At, 1, 0); PG8_STAGE(PG8_SA(0, 1), a2 + hstepA, voffA);
;             PG8_WAIT_V(8); PG8_WAIT_L(0); PG8_BAR; PG8_MMA(0, 0, At, B0); PG8_MMA(0, 1, At, B1); PG8_BAR; PG8_SCHED;
.Lt1_574_2:
	s_mov_b32 s100, 0
	s_waitcnt lgkmcnt(0)
	s_barrier
	s_setprio 1
	s_waitcnt lgkmcnt(0)
	v_mfma_f32_16x16x32_bf16 v[62:65], v[144:147], v[186:189], v[62:65]
	v_mfma_f32_16x16x32_bf16 v[58:61], v[162:165], v[186:189], v[58:61]
	v_mfma_f32_16x16x32_bf16 v[46:49], v[144:147], v[204:207], v[46:49]
	v_mfma_f32_16x16x32_bf16 v[42:45], v[162:165], v[204:207], v[42:45]
	v_mfma_f32_16x16x32_bf16 v[30:33], v[144:147], v[212:215], v[30:33]
	v_mfma_f32_16x16x32_bf16 v[26:29], v[162:165], v[212:215], v[26:29]
	v_mfma_f32_16x16x32_bf16 v[14:17], v[144:147], v[220:223], v[14:17]
	v_mfma_f32_16x16x32_bf16 v[10:13], v[162:165], v[220:223], v[10:13]
	v_mfma_f32_16x16x32_bf16 v[62:65], v[158:161], v[190:193], v[62:65]
	v_mfma_f32_16x16x32_bf16 v[58:61], v[166:169], v[190:193], v[58:61]
	v_mfma_f32_16x16x32_bf16 v[46:49], v[158:161], v[208:211], v[46:49]
	v_mfma_f32_16x16x32_bf16 v[42:45], v[166:169], v[208:211], v[42:45]
	v_mfma_f32_16x16x32_bf16 v[30:33], v[158:161], v[216:219], v[30:33]
	v_mfma_f32_16x16x32_bf16 v[26:29], v[166:169], v[216:219], v[26:29]
	v_mfma_f32_16x16x32_bf16 v[14:17], v[158:161], v[230:233], v[14:17]
	v_mfma_f32_16x16x32_bf16 v[10:13], v[166:169], v[230:233], v[10:13]
	s_setprio 0
	s_setprio 1
	v_mfma_f32_16x16x32_bf16 v[54:57], v[170:173], v[186:189], v[54:57]
	v_mfma_f32_16x16x32_bf16 v[50:53], v[178:181], v[186:189], v[50:53]
	v_mfma_f32_16x16x32_bf16 v[38:41], v[170:173], v[204:207], v[38:41]
	v_mfma_f32_16x16x32_bf16 v[34:37], v[178:181], v[204:207], v[34:37]
	v_mfma_f32_16x16x32_bf16 v[22:25], v[170:173], v[212:215], v[22:25]
	v_mfma_f32_16x16x32_bf16 v[18:21], v[178:181], v[212:215], v[18:21]
	v_mfma_f32_16x16x32_bf16 v[6:9], v[170:173], v[220:223], v[6:9]
	v_mfma_f32_16x16x32_bf16 v[2:5], v[178:181], v[220:223], v[2:5]
	v_mfma_f32_16x16x32_bf16 v[54:57], v[174:177], v[190:193], v[54:57]
	v_mfma_f32_16x16x32_bf16 v[50:53], v[182:185], v[190:193], v[50:53]
	v_mfma_f32_16x16x32_bf16 v[38:41], v[174:177], v[208:211], v[38:41]
	v_mfma_f32_16x16x32_bf16 v[34:37], v[182:185], v[208:211], v[34:37]
	v_mfma_f32_16x16x32_bf16 v[22:25], v[174:177], v[216:219], v[22:25]
	v_mfma_f32_16x16x32_bf16 v[18:21], v[182:185], v[216:219], v[18:21]
	v_mfma_f32_16x16x32_bf16 v[6:9], v[174:177], v[230:233], v[6:9]
	v_mfma_f32_16x16x32_bf16 v[2:5], v[182:185], v[230:233], v[2:5]
	s_setprio 0
	s_barrier
	s_add_i32 s82, 0, 0x18000
	v_add_u32_e32 v157, s82, v151
	s_add_i32 s83, 0, 0x1c000
	ds_read_b128 v[144:147], v157
	ds_read_b128 v[158:161], v157 offset:1024
	ds_read_b128 v[162:165], v157 offset:2048
	ds_read_b128 v[166:169], v157 offset:3072
	v_add_u32_e32 v157, s83, v151
	ds_read_b128 v[170:173], v157
	ds_read_b128 v[174:177], v157 offset:1024
	ds_read_b128 v[178:181], v157 offset:2048
	ds_read_b128 v[182:185], v157 offset:3072
	s_add_u32 s14, s72, 0x80000
	s_addc_u32 s15, s73, 0
	s_mov_b32 m0, s75
	v_lshl_add_u64 v[200:201], s[14:15], 0, v[130:131]
	ds_read_b128 v[186:189], v156 offset:32768
	ds_read_b128 v[190:193], v156 offset:33792
	ds_read_b128 v[204:207], v156 offset:34816
	ds_read_b128 v[208:211], v156 offset:35840
	ds_read_b128 v[212:215], v156 offset:36864
	ds_read_b128 v[216:219], v156 offset:37888
	ds_read_b128 v[220:223], v156 offset:38912
	ds_read_b128 v[230:233], v156 offset:39936
	global_load_lds_dwordx4 v[200:201], off
	v_lshl_add_u64 v[200:201], s[14:15], 0, v[132:133]
	s_mov_b32 m0, s76
	s_nop 0
	global_load_lds_dwordx4 v[200:201], off
	s_waitcnt vmcnt(8)
	s_waitcnt lgkmcnt(0)
	s_barrier
	s_setprio 1
	s_waitcnt lgkmcnt(0)
	v_mfma_f32_16x16x32_bf16 v[126:129], v[144:147], v[186:189], v[126:129]
	v_mfma_f32_16x16x32_bf16 v[122:125], v[162:165], v[186:189], v[122:125]
	v_mfma_f32_16x16x32_bf16 v[110:113], v[144:147], v[204:207], v[110:113]
	v_mfma_f32_16x16x32_bf16 v[106:109], v[162:165], v[204:207], v[106:109]
	v_mfma_f32_16x16x32_bf16 v[94:97], v[144:147], v[212:215], v[94:97]
	v_mfma_f32_16x16x32_bf16 v[90:93], v[162:165], v[212:215], v[90:93]
	v_mfma_f32_16x16x32_bf16 v[78:81], v[144:147], v[220:223], v[78:81]
	v_mfma_f32_16x16x32_bf16 v[74:77], v[162:165], v[220:223], v[74:77]
	v_mfma_f32_16x16x32_bf16 v[126:129], v[158:161], v[190:193], v[126:129]
	v_mfma_f32_16x16x32_bf16 v[122:125], v[166:169], v[190:193], v[122:125]
	v_mfma_f32_16x16x32_bf16 v[110:113], v[158:161], v[208:211], v[110:113]
	v_mfma_f32_16x16x32_bf16 v[106:109], v[166:169], v[208:211], v[106:109]
	v_mfma_f32_16x16x32_bf16 v[94:97], v[158:161], v[216:219], v[94:97]
	v_mfma_f32_16x16x32_bf16 v[90:93], v[166:169], v[216:219], v[90:93]
	v_mfma_f32_16x16x32_bf16 v[78:81], v[158:161], v[230:233], v[78:81]
	v_mfma_f32_16x16x32_bf16 v[74:77], v[166:169], v[230:233], v[74:77]
	s_setprio 0
	s_setprio 1
	v_mfma_f32_16x16x32_bf16 v[118:121], v[170:173], v[186:189], v[118:121]
	v_mfma_f32_16x16x32_bf16 v[114:117], v[178:181], v[186:189], v[114:117]
	v_mfma_f32_16x16x32_bf16 v[102:105], v[170:173], v[204:207], v[102:105]
	v_mfma_f32_16x16x32_bf16 v[98:101], v[178:181], v[204:207], v[98:101]
	v_mfma_f32_16x16x32_bf16 v[86:89], v[170:173], v[212:215], v[86:89]
	v_mfma_f32_16x16x32_bf16 v[82:85], v[178:181], v[212:215], v[82:85]
	v_mfma_f32_16x16x32_bf16 v[70:73], v[170:173], v[220:223], v[70:73]
	v_mfma_f32_16x16x32_bf16 v[66:69], v[178:181], v[220:223], v[66:69]
	v_mfma_f32_16x16x32_bf16 v[118:121], v[174:177], v[190:193], v[118:121]
	v_mfma_f32_16x16x32_bf16 v[114:117], v[182:185], v[190:193], v[114:117]
	v_mfma_f32_16x16x32_bf16 v[102:105], v[174:177], v[208:211], v[102:105]
	v_mfma_f32_16x16x32_bf16 v[98:101], v[182:185], v[208:211], v[98:101]
	v_mfma_f32_16x16x32_bf16 v[86:89], v[174:177], v[216:219], v[86:89]
	v_mfma_f32_16x16x32_bf16 v[82:85], v[182:185], v[216:219], v[82:85]
	v_mfma_f32_16x16x32_bf16 v[70:73], v[174:177], v[230:233], v[70:73]
	v_mfma_f32_16x16x32_bf16 v[66:69], v[182:185], v[230:233], v[66:69]
	s_setprio 0
	s_barrier
; #define PG8_STAGE(bufoff, gbase, voff) do { _Pragma("unroll") for (int _i = 0; _i < 2; ++_i) \
;         __builtin_amdgcn_global_load_lds((const unsigned*)((const char*)(gbase) + (voff)[_i]), (LAS unsigned*)(lds + (bufoff) + ldsw + _i * 8192), 16, 0, 0); } while (0)
; #define PG8_LDA(dst, b, h) do { _Pragma("unroll") for (int m = 0; m < 4; ++m) _Pragma("unroll") for (int k = 0; k < 2; ++k) dst[m][k] = *(const LAS bf16x8*)(lds + PG8_SA(b, h) + aoff + m * 2048 + k * 1024); } while (0)
; #define PG8_MMA(ai, bj, At, Bt) do { __builtin_amdgcn_s_setprio(1); _Pragma("unroll") for (int m = 0; m < 4; ++m) _Pragma("unroll") for (int n = 0; n < 2; ++n) _Pragma("unroll") for (int k = 0; k < 2; ++k) \
;         acc[ai][bj][m][n] = __builtin_amdgcn_mfma_f32_16x16x32_bf16(Bt[n][k], At[m][k], acc[ai][bj][m][n], 0, 0, 0); __builtin_amdgcn_s_setprio(0); } while (0)
; #define PG8_WAIT_V(n) asm volatile("s_waitcnt vmcnt(" #n ")" ::: "memory")
; #define PG8_WAIT_L(n) asm volatile("s_waitcnt lgkmcnt(" #n ")" ::: "memory")
; #define PG8_BAR __builtin_amdgcn_s_barrier()
; #define PG8_SCHED __builtin_amdgcn_sched_barrier(0)
; template <class Epi, class Sched>
; __device__ __forceinline__ void gemm_phase(LAS unsigned char* lds, const Gemm g, const Sched& S, const Epi& E, const int tid) {
;     ...
;             PG8_LDA(At, 1, 1); PG8_STAGE(PG8_SB(1, 0), b3, voffB); PG8_STAGE(PG8_SB(1, 1), b3 + hstepB, voffB); PG8_STAGE(PG8_SA(1, 0), a3, voffA);
;             PG8_WAIT_V(8); PG8_WAIT_L(0); PG8_BAR; PG8_MMA(1, 0, At, B0); PG8_MMA(1, 1, At, B1); PG8_BAR; PG8_SCHED;
;         }
;         if (wr == 0) PG8_BAR;
;         E(acc, cur, wr, wc, fr, fq);
;         if (!has_next) break;
;         if (E.zero_after(cur))
	s_add_i32 s14, s82, s56
	v_lshl_add_u64 v[148:149], v[148:149], 0, s[90:91]
	s_mov_b32 m0, s14
	ds_read_b128 v[186:189], v156 offset:49152
	ds_read_b128 v[190:193], v156 offset:50176
	ds_read_b128 v[204:207], v156 offset:51200
	ds_read_b128 v[208:211], v156 offset:52224
	ds_read_b128 v[212:215], v156 offset:53248
	ds_read_b128 v[216:219], v156 offset:54272
	ds_read_b128 v[220:223], v156 offset:55296
	ds_read_b128 v[230:233], v156 offset:56320
	global_load_lds_dwordx4 v[148:149], off
	s_add_i32 m0, s14, 0x2000
	s_add_u32 s14, s70, 0x80080
	v_lshl_add_u64 v[148:149], v[194:195], 0, s[90:91]
	s_addc_u32 s15, s71, 0
	s_add_i32 s70, s83, s56
	global_load_lds_dwordx4 v[148:149], off
	v_lshl_add_u64 v[148:149], s[14:15], 0, v[0:1]
	s_mov_b32 m0, s70
	s_nop 0
	global_load_lds_dwordx4 v[148:149], off
	v_lshl_add_u64 v[148:149], s[14:15], 0, v[134:135]
	s_add_i32 m0, s70, 0x2000
	s_nop 0
	global_load_lds_dwordx4 v[148:149], off
	v_lshl_add_u64 v[148:149], v[196:197], 0, s[90:91]
	s_mov_b32 m0, s77
	s_nop 0
	global_load_lds_dwordx4 v[148:149], off
	v_lshl_add_u64 v[148:149], v[198:199], 0, s[90:91]
	s_mov_b32 m0, s78
	s_nop 0
	global_load_lds_dwordx4 v[148:149], off
	s_waitcnt vmcnt(8)
	s_waitcnt lgkmcnt(0)
	s_barrier
	s_setprio 1
	s_waitcnt lgkmcnt(0)
	v_mfma_f32_16x16x32_bf16 v[62:65], v[144:147], v[186:189], v[62:65]
	v_mfma_f32_16x16x32_bf16 v[58:61], v[162:165], v[186:189], v[58:61]
	v_mfma_f32_16x16x32_bf16 v[46:49], v[144:147], v[204:207], v[46:49]
	v_mfma_f32_16x16x32_bf16 v[42:45], v[162:165], v[204:207], v[42:45]
	v_mfma_f32_16x16x32_bf16 v[30:33], v[144:147], v[212:215], v[30:33]
	v_mfma_f32_16x16x32_bf16 v[26:29], v[162:165], v[212:215], v[26:29]
	v_mfma_f32_16x16x32_bf16 v[14:17], v[144:147], v[220:223], v[14:17]
	v_mfma_f32_16x16x32_bf16 v[10:13], v[162:165], v[220:223], v[10:13]
	v_mfma_f32_16x16x32_bf16 v[62:65], v[158:161], v[190:193], v[62:65]
	v_mfma_f32_16x16x32_bf16 v[58:61], v[166:169], v[190:193], v[58:61]
	v_mfma_f32_16x16x32_bf16 v[46:49], v[158:161], v[208:211], v[46:49]
	v_mfma_f32_16x16x32_bf16 v[42:45], v[166:169], v[208:211], v[42:45]
	v_mfma_f32_16x16x32_bf16 v[30:33], v[158:161], v[216:219], v[30:33]
	v_mfma_f32_16x16x32_bf16 v[26:29], v[166:169], v[216:219], v[26:29]
	v_mfma_f32_16x16x32_bf16 v[14:17], v[158:161], v[230:233], v[14:17]
	v_mfma_f32_16x16x32_bf16 v[10:13], v[166:169], v[230:233], v[10:13]
	s_setprio 0
	s_setprio 1
	v_mfma_f32_16x16x32_bf16 v[54:57], v[170:173], v[186:189], v[54:57]
	v_mfma_f32_16x16x32_bf16 v[50:53], v[178:181], v[186:189], v[50:53]
	v_mfma_f32_16x16x32_bf16 v[38:41], v[170:173], v[204:207], v[38:41]
	v_mfma_f32_16x16x32_bf16 v[34:37], v[178:181], v[204:207], v[34:37]
	v_mfma_f32_16x16x32_bf16 v[22:25], v[170:173], v[212:215], v[22:25]
	v_mfma_f32_16x16x32_bf16 v[18:21], v[178:181], v[212:215], v[18:21]
	v_mfma_f32_16x16x32_bf16 v[6:9], v[170:173], v[220:223], v[6:9]
	v_mfma_f32_16x16x32_bf16 v[2:5], v[178:181], v[220:223], v[2:5]
	v_mfma_f32_16x16x32_bf16 v[54:57], v[174:177], v[190:193], v[54:57]
	v_mfma_f32_16x16x32_bf16 v[50:53], v[182:185], v[190:193], v[50:53]
	v_mfma_f32_16x16x32_bf16 v[38:41], v[174:177], v[208:211], v[38:41]
	v_mfma_f32_16x16x32_bf16 v[34:37], v[182:185], v[208:211], v[34:37]
	v_mfma_f32_16x16x32_bf16 v[22:25], v[174:177], v[216:219], v[22:25]
	v_mfma_f32_16x16x32_bf16 v[18:21], v[182:185], v[216:219], v[18:21]
	v_mfma_f32_16x16x32_bf16 v[6:9], v[174:177], v[230:233], v[6:9]
	v_mfma_f32_16x16x32_bf16 v[2:5], v[182:185], v[230:233], v[2:5]
	s_setprio 0
	s_barrier
	s_add_i32 s81, s81, 2
	s_add_u32 s79, s79, 0x100
	s_addc_u32 s80, s80, 0
	s_add_u32 s44, s44, 0x100
	s_addc_u32 s45, s45, 0
	s_cmp_gt_u32 s81, 29
	s_cbranch_scc0 .LBB1_574
	s_mov_b32 s100, 1
	s_and_b64 vcc, exec, s[36:37]
	s_cbranch_vccz .LBB1_577
	s_barrier
